# GLA: waves 4-7 run at static s_setprio 1 through the unit loop
# speedup vs baseline: 1.0073x; 1.0047x over previous
; __device__ __forceinline__ int opaque_tid() { int t = threadIdx.x; asm volatile("" : "+v"(t)); return t; }
; __device__ __forceinline__ void gla_phase(LAS unsigned char* lds, const bf16_t* P, const float* hn, bf16_t* O, int G, int wg) {
;     const int tid = opaque_tid(), lane = tid & 63, wid = tid >> 6, fr = lane & 15, fq = lane >> 4;
;     constexpr int QT = 0, KT = 16384, ST = 32768, KTT = 65536, VT = 81920, AM = 98304, PART = 106496, SSQX = 110592, HNL = 111104;
;     const int LK0 = fr * 256 + ((fq ^ (fr & 3)) << 4) + ((fr >> 2) << 6);
;     const int LS0 = fr * 128 + ((fq ^ ((fr >> 1) & 3)) << 4) + ((fr >> 3) << 6);
;     constexpr float LOG2E = 1.4426950408889634f;
;     const int dp = tid & 63, tq = tid >> 6;
;     const int tt = wid & 3, eh = wid >> 2;
;     ...
;     for (int unit = wg; unit < NB * NH; unit += G) {
.LBB0_1393:
	s_andn2_b64 vcc, exec, s[0:1]
	s_cbranch_vccnz .LBB0_1618
	v_readlane_b32 s0, v255, 12
	s_cmp_eq_u32 s0, 0
	v_readlane_b32 s0, v255, 10
	s_cselect_b64 s[38:39], -1, 0
	v_readlane_b32 s1, v255, 11
	v_readlane_b32 s8, v253, 48
	s_or_b64 s[0:1], s[38:39], s[0:1]
	v_readlane_b32 s9, v253, 49
	s_and_b64 s[8:9], s[0:1], s[8:9]
	s_mov_b64 s[0:1], -1
	s_and_b64 vcc, exec, s[8:9]
	s_cbranch_vccnz .LBB0_1416
	v_readlane_b32 s0, v253, 50
	v_readlane_b32 s1, v253, 51
	v_readlane_b32 s80, v252, 36
	v_mov_b32_e32 v0, v210
	s_and_b64 vcc, exec, s[0:1]
	v_readlane_b32 s81, v252, 37
	s_cbranch_vccz .LBB0_1520
	v_readlane_b32 s0, v255, 10
	v_readlane_b32 s1, v255, 11
	v_and_b32_e32 v7, 15, v0
	v_bfe_u32 v10, v0, 1, 3
	v_bfe_u32 v4, v0, 4, 2
	s_and_b64 s[0:1], s[0:1], exec
	v_readlane_b32 s40, v252, 0
	s_waitcnt vmcnt(0)
	v_ashrrev_i32_e32 v3, 6, v0
	s_waitcnt lgkmcnt(0)
	v_bitop3_b32 v1, v10, v4, 3 bitop3:0x6c
	v_lshlrev_b32_e32 v2, 7, v7
	s_cselect_b32 s0, 0x200, 0
	v_readlane_b32 s52, v252, 12
	v_and_b32_e32 v5, 3, v3
	v_lshl_or_b32 v12, v1, 4, v2
	v_bitop3_b32 v1, v4, v0, 3 bitop3:0x78
	v_lshlrev_b32_e32 v22, 1, v3
	v_bfe_u32 v23, v0, 5, 1
	v_readlane_b32 s53, v252, 13
	s_add_u32 s0, s52, s0
	v_and_or_b32 v1, v0, 12, v1
	v_lshlrev_b32_e32 v15, 8, v7
	v_bitop3_b32 v22, v22, v7, v23 bitop3:0x36
	v_lshrrev_b32_e32 v24, 1, v0
	v_lshlrev_b32_e32 v29, 1, v5
	v_readlane_b32 s41, v252, 1
	s_addc_u32 s1, s53, 0
	v_lshlrev_b32_e32 v14, 4, v1
	s_movk_i32 s16, 0x80
	v_lshlrev_b32_e32 v17, 2, v0
	v_readlane_b32 s8, v254, 59
	v_ashrrev_i32_e32 v1, 31, v0
	v_lshlrev_b32_e32 v82, 3, v3
	v_add_u32_e32 v21, 0, v15
	v_lshlrev_b32_e32 v22, 4, v22
	v_and_b32_e32 v24, 8, v24
	v_bitop3_b32 v10, v29, v10, v23 bitop3:0x36
	v_readlane_b32 s44, v252, 4
	v_readlane_b32 s45, v252, 5
	v_readlane_b32 s46, v252, 6
	v_readlane_b32 s47, v252, 7
	v_readlane_b32 s48, v252, 8
	v_readlane_b32 s49, v252, 9
	v_readlane_b32 s50, v252, 10
	v_readlane_b32 s51, v252, 11
	v_readlane_b32 s54, v252, 14
	v_readlane_b32 s55, v252, 15
	v_and_b32_e32 v11, 63, v0
	v_lshlrev_b32_e32 v13, 3, v0
	v_ashrrev_i32_e32 v16, 8, v0
	v_cmp_gt_i32_e64 s[40:41], s16, v0
	v_add_u32_e32 v145, s8, v17
	v_lshl_add_u64 v[80:81], v[0:1], 2, s[0:1]
	v_ashrrev_i32_e32 v83, 31, v82
	s_add_i32 s8, 0, 0x1a000
	s_add_i32 s0, 0, 0x1b000
	v_and_b32_e32 v147, 0xffffff30, v0
	v_and_b32_e32 v6, 16, v0
	v_and_b32_e32 v19, 0xffffffc0, v0
	v_and_b32_e32 v20, 48, v0
	v_add3_u32 v149, v21, v22, v24
	v_bfe_u32 v21, v0, 2, 4
	v_bitop3_b32 v25, v3, v0, 7 bitop3:0x78
	v_lshlrev_b32_e32 v10, 4, v10
	s_add_i32 s1, 0, 0x18000
	v_and_b32_e32 v0, 0xffffff00, v0
	v_lshlrev_b32_e32 v2, 1, v11
	v_lshlrev_b64 v[84:85], 13, v[82:83]
	v_lshlrev_b32_e32 v83, 3, v11
	v_lshl_add_u32 v1, v3, 9, s8
	v_lshlrev_b32_e32 v22, 8, v11
	v_add3_u32 v10, s1, v10, v24
	v_lshlrev_b32_e32 v23, 11, v3
	v_cmp_gt_u32_e64 s[44:45], 16, v11
	v_add_u32_e32 v0, s0, v0
	v_lshlrev_b32_e32 v11, 6, v5
	v_lshlrev_b32_e32 v24, 2, v7
	v_cmp_lt_i32_e64 s[46:47], 0, v3
	v_cmp_lt_i32_e64 s[48:49], 1, v3
	v_cmp_lt_i32_e64 s[50:51], 2, v3
	v_cmp_lt_i32_e64 s[52:53], 3, v3
	v_cmp_lt_i32_e64 s[54:55], 4, v3
	v_cmp_lt_i32_e64 s[56:57], 5, v3
	v_cmp_lt_i32_e64 s[58:59], 6, v3
	v_bitop3_b32 v3, v82, v21, 8 bitop3:0x6c
	v_and_b32_e32 v17, 12, v17
	s_add_i32 s9, 0, 0x10000
	v_add3_u32 v156, v0, v11, v24
	v_lshlrev_b32_e32 v3, 4, v3
	v_or_b32_e32 v11, 1, v82
	v_add_u32_e32 v155, s9, v23
	v_or3_b32 v3, v3, v23, v17
	v_lshlrev_b32_e32 v23, 8, v11
	v_bitop3_b32 v11, v11, v21, 9 bitop3:0x6c
	v_lshlrev_b32_e32 v11, 4, v11
	v_or3_b32 v11, v11, v23, v17
	v_or_b32_e32 v23, 2, v82
	v_lshlrev_b32_e32 v24, 8, v23
	v_bitop3_b32 v23, v23, v21, 10 bitop3:0x6c
	v_lshlrev_b32_e32 v23, 4, v23
	v_or3_b32 v23, v23, v24, v17
	v_or_b32_e32 v24, 3, v82
	v_lshlrev_b32_e32 v29, 8, v24
	v_bitop3_b32 v24, v24, v21, 11 bitop3:0x6c
	v_lshlrev_b32_e32 v24, 4, v24
	v_or3_b32 v24, v24, v29, v17
	v_or_b32_e32 v29, 4, v82
	v_lshlrev_b32_e32 v30, 8, v29
	v_bitop3_b32 v29, v29, v21, 12 bitop3:0x6c
	v_lshlrev_b32_e32 v29, 4, v29
	v_or3_b32 v29, v29, v30, v17
	v_or_b32_e32 v30, 5, v82
	v_lshlrev_b32_e32 v31, 8, v30
	v_bitop3_b32 v30, v30, v21, 13 bitop3:0x6c
	v_lshlrev_b32_e32 v30, 4, v30
	v_lshlrev_b32_e32 v18, 4, v5
	v_or3_b32 v30, v30, v31, v17
	v_or_b32_e32 v31, 6, v82
	v_or_b32_e32 v86, v18, v7
	v_lshlrev_b32_e32 v32, 8, v31
	v_bitop3_b32 v31, v31, v21, 14 bitop3:0x6c
	v_readlane_b32 s42, v252, 2
	v_readlane_b32 s43, v252, 3
	v_lshl_add_u32 v146, v86, 2, s0
	v_lshlrev_b32_e32 v4, 2, v4
	v_lshl_add_u32 v22, v25, 4, v22
	v_lshlrev_b32_e32 v25, 1, v16
	v_lshlrev_b32_e32 v31, 4, v31
	s_movk_i32 s0, 0xc0
	v_or_b32_e32 v144, v14, v15
	v_add_u32_e32 v8, 12, v4
	v_cmp_eq_u32_e64 s[42:43], 0, v6
	v_or_b32_e32 v18, v18, v4
	v_or3_b32 v31, v31, v32, v17
	v_or_b32_e32 v32, 7, v82
	v_bitop3_b32 v157, v14, 64, v15 bitop3:0x36
	v_bitop3_b32 v158, v14, s16, v15 bitop3:0x36
	v_bitop3_b32 v159, v14, s0, v15 bitop3:0x36
	v_or_b32_e32 v14, 1, v25
	v_cndmask_b32_e64 v6, v8, v4, s[42:43]
	v_lshl_add_u32 v150, v5, 12, 0
	v_or_b32_e32 v27, 2, v18
	v_or_b32_e32 v28, 3, v18
	v_lshl_add_u32 v153, v5, 11, s1
	v_bitop3_b32 v21, v32, v21, 15 bitop3:0x6c
	v_cmp_ge_i32_e64 s[60:61], v25, v5
	v_cmp_ge_i32_e64 s[62:63], v14, v5
	v_lshl_or_b32 v5, v16, 5, v7
	v_and_or_b32 v87, v13, 64, v12
	v_lshlrev_b32_e32 v88, 6, v16
	v_lshlrev_b32_e32 v174, 1, v6
	v_lshlrev_b32_e32 v148, 14, v16
	v_lshlrev_b32_e32 v26, 13, v16
	s_add_i32 s1, 0, 0x14000
; __device__ __forceinline__ void gla_phase(LAS unsigned char* lds, const bf16_t* P, const float* hn, bf16_t* O, int G, int wg) {
;     ...
;     for (int unit = wg; unit < NB * NH; unit += G) {
;     ...
;         __syncthreads();
;         GLA_EPILOGUE(31);
	v_lshlrev_b32_e32 v33, 8, v32
	v_lshlrev_b32_e32 v21, 4, v21
	v_cmp_lt_i32_e64 s[64:65], v5, v18
	v_cmp_gt_i32_e64 s[66:67], v5, v18
	v_cmp_lt_i32_e64 s[68:69], v5, v27
	v_cmp_lt_i32_e64 s[70:71], v5, v28
	v_lshlrev_b32_e32 v7, 7, v5
	v_or_b32_e32 v5, 16, v5
	v_bitop3_b32 v160, v12, 64, v13 bitop3:0x34
	v_lshl_add_u64 v[8:9], s[80:81], 0, v[174:175]
	v_add_u32_e32 v20, s8, v20
	v_ashrrev_i32_e32 v89, 31, v88
	v_xor_b32_e32 v0, 0x4000, v148
	v_or3_b32 v17, v21, v33, v17
	v_cmp_lt_i32_e64 s[72:73], v5, v18
	v_cmp_gt_i32_e64 s[74:75], v5, v18
	v_cmp_lt_i32_e64 s[76:77], v5, v27
	v_cmp_lt_i32_e64 s[78:79], v5, v28
	v_lshlrev_b32_e32 v5, 7, v5
	v_xor_b32_e32 v12, 0x2000, v26
	v_add_u32_e32 v13, s1, v87
	v_add_u32_e32 v14, s1, v160
	v_add_u32_e32 v151, 0, v26
	v_add_u32_e32 v152, 0, v148
	v_add_u32_e32 v154, s1, v26
	v_lshl_add_u64 v[90:91], v[88:89], 1, v[8:9]
	v_lshlrev_b32_e32 v92, 1, v2
	v_add_u32_e32 v161, v1, v83
	v_lshlrev_b32_e32 v94, 1, v4
	v_add_u32_e32 v162, v149, v0
	v_add_u32_e32 v163, 0, v3
	v_add_u32_e32 v164, 0, v11
	v_add_u32_e32 v165, 0, v23
	v_add_u32_e32 v166, 0, v24
	v_add_u32_e32 v167, 0, v29
	v_add_u32_e32 v168, 0, v30
	v_add_u32_e32 v169, 0, v31
	v_add_u32_e32 v170, 0, v17
	v_add_u32_e32 v171, 0, v22
	v_add_u32_e32 v180, v10, v7
	v_add_u32_e32 v181, v10, v5
	v_add_u32_e32 v182, v13, v12
	v_add_u32_e32 v183, v14, v12
	v_lshlrev_b32_e32 v96, 1, v6
	v_add_u32_e32 v184, v20, v19
	s_and_b32 s9, s2, 7
	s_lshl_b32 s9, s9, 4
	s_lshr_b32 s0, s2, 3
	s_or_b32 s9, s9, s0
	s_and_b32 s0, s28, 0x7f
	s_cmp_eq_u32 s0, 0
	s_cselect_b32 s9, s9, s2
	v_readfirstlane_b32 s0, v210
	s_cmp_lt_u32 s0, 0x100
	s_cbranch_scc1 .Lgla_prio_done
	s_setprio 1
.Lgla_prio_done:
	s_branch .LBB0_1398
.LBB0_1397:
	s_barrier
	ds_read2st64_b32 v[16:17], v146 offset1:1
	v_mov_b32_e32 v97, v175
	s_mov_b64 s[0:1], 0x3e0000
	s_add_i32 s9, s9, s28
	s_cmpk_gt_i32 s9, 0x7f
	s_waitcnt lgkmcnt(0)
	v_add_f32_e32 v16, v16, v17
	v_add_u32_e32 v17, 0, v147
	v_fmamk_f32 v16, v16, 0x3c000000, v211
	v_add_u32_e32 v17, 0x1b200, v17
	v_rsq_f32_e32 v16, v16
	ds_read_b128 v[18:21], v17
	v_pk_mul_f32 v[12:13], v[12:13], v[16:17] op_sel_hi:[1,0]
	v_pk_mul_f32 v[8:9], v[8:9], v[16:17] op_sel_hi:[1,0]
	s_waitcnt lgkmcnt(0)
	v_pk_mul_f32 v[12:13], v[18:19], v[12:13]
	s_waitcnt vmcnt(3)
	v_lshlrev_b32_e32 v18, 16, v142
	v_and_b32_e32 v19, 0xffff0000, v142
	v_pk_mul_f32 v[12:13], v[12:13], v[18:19]
	v_pk_mul_f32 v[4:5], v[4:5], v[16:17] op_sel_hi:[1,0]
	v_cvt_pk_bf16_f32 v18, v12, v13
	v_pk_mul_f32 v[12:13], v[14:15], v[16:17] op_sel_hi:[1,0]
	v_lshlrev_b32_e32 v14, 16, v143
	v_pk_mul_f32 v[12:13], v[20:21], v[12:13]
	v_and_b32_e32 v15, 0xffff0000, v143
	v_pk_mul_f32 v[12:13], v[12:13], v[14:15]
	v_pk_mul_f32 v[0:1], v[0:1], v[16:17] op_sel_hi:[1,0]
	v_cvt_pk_bf16_f32 v19, v12, v13
	ds_read_b128 v[12:15], v17 offset:64
	s_waitcnt lgkmcnt(0)
	v_pk_mul_f32 v[8:9], v[12:13], v[8:9]
	s_waitcnt vmcnt(2)
	v_lshlrev_b32_e32 v12, 16, v140
	v_and_b32_e32 v13, 0xffff0000, v140
	v_pk_mul_f32 v[8:9], v[8:9], v[12:13]
	s_nop 0
	v_cvt_pk_bf16_f32 v12, v8, v9
	v_pk_mul_f32 v[8:9], v[10:11], v[16:17] op_sel_hi:[1,0]
	v_lshlrev_b32_e32 v10, 16, v141
	v_pk_mul_f32 v[8:9], v[14:15], v[8:9]
	v_and_b32_e32 v11, 0xffff0000, v141
	v_pk_mul_f32 v[8:9], v[8:9], v[10:11]
	s_nop 0
	v_cvt_pk_bf16_f32 v13, v8, v9
	ds_read_b128 v[8:11], v17 offset:128
	s_waitcnt lgkmcnt(0)
	v_pk_mul_f32 v[4:5], v[8:9], v[4:5]
	s_waitcnt vmcnt(1)
	v_lshlrev_b32_e32 v8, 16, v114
	v_and_b32_e32 v9, 0xffff0000, v114
	v_pk_mul_f32 v[4:5], v[4:5], v[8:9]
	s_nop 0
	v_cvt_pk_bf16_f32 v8, v4, v5
	v_pk_mul_f32 v[4:5], v[6:7], v[16:17] op_sel_hi:[1,0]
	v_lshlrev_b32_e32 v6, 16, v115
	v_pk_mul_f32 v[4:5], v[10:11], v[4:5]
	v_and_b32_e32 v7, 0xffff0000, v115
	v_pk_mul_f32 v[4:5], v[4:5], v[6:7]
	s_nop 0
	v_cvt_pk_bf16_f32 v9, v4, v5
	ds_read_b128 v[4:7], v17 offset:192
	s_waitcnt lgkmcnt(0)
	v_pk_mul_f32 v[0:1], v[0:1], v[4:5]
	s_waitcnt vmcnt(0)
	v_lshlrev_b32_e32 v4, 16, v100
	v_and_b32_e32 v5, 0xffff0000, v100
	v_pk_mul_f32 v[0:1], v[0:1], v[4:5]
	s_nop 0
	v_cvt_pk_bf16_f32 v10, v0, v1
	v_pk_mul_f32 v[0:1], v[2:3], v[16:17] op_sel_hi:[1,0]
	v_lshlrev_b32_e32 v2, 16, v101
	v_pk_mul_f32 v[0:1], v[0:1], v[6:7]
	v_and_b32_e32 v3, 0xffff0000, v101
	v_pk_mul_f32 v[0:1], v[0:1], v[2:3]
	s_nop 0
	v_cvt_pk_bf16_f32 v11, v0, v1
	v_lshlrev_b64 v[0:1], 11, v[98:99]
	v_lshl_add_u64 v[0:1], s[80:81], 0, v[0:1]
	v_lshl_add_u64 v[0:1], v[0:1], 0, s[16:17]
	v_lshl_add_u64 v[4:5], v[0:1], 0, v[96:97]
	v_cndmask_b32_e64 v0, v18, v12, s[42:43]
	v_cndmask_b32_e64 v1, v19, v13, s[42:43]
	ds_bpermute_b32 v0, v95, v0
	ds_bpermute_b32 v1, v95, v1
	v_lshl_add_u64 v[4:5], v[88:89], 1, v[4:5]
	v_lshl_add_u64 v[6:7], v[4:5], 0, s[0:1]
	s_mov_b32 s0, 0x3e0000
	v_add_co_u32_e32 v4, vcc, s0, v4
	s_waitcnt lgkmcnt(0)
	v_cndmask_b32_e64 v3, v13, v1, s[42:43]
	v_cndmask_b32_e64 v2, v12, v0, s[42:43]
	v_cndmask_b32_e64 v1, v1, v19, s[42:43]
	v_cndmask_b32_e64 v0, v0, v18, s[42:43]
	v_addc_co_u32_e32 v5, vcc, 0, v5, vcc
	global_store_dwordx4 v[4:5], v[0:3], off
	s_nop 1
	v_cndmask_b32_e64 v0, v8, v10, s[42:43]
	v_cndmask_b32_e64 v1, v9, v11, s[42:43]
	ds_bpermute_b32 v0, v95, v0
	ds_bpermute_b32 v1, v95, v1
	s_waitcnt lgkmcnt(1)
	v_cndmask_b32_e64 v2, v10, v0, s[42:43]
	s_waitcnt lgkmcnt(0)
	v_cndmask_b32_e64 v3, v11, v1, s[42:43]
	v_cndmask_b32_e64 v1, v1, v9, s[42:43]
	v_cndmask_b32_e64 v0, v0, v8, s[42:43]
	global_store_dwordx4 v[6:7], v[0:3], off offset:64
	s_cbranch_scc1 .Lgla_exit_prio

; __device__ __forceinline__ void gla_phase(LAS unsigned char* lds, const bf16_t* P, const float* hn, bf16_t* O, int G, int wg) {
;     ...
;         __syncthreads();
;         GLA_EPILOGUE(31);
;     }
.LBB0_1518:
	v_or_b32_e32 v24, 14, v32
	v_ashrrev_i32_e32 v25, 31, v24
	v_lshlrev_b64 v[24:25], 14, v[24:25]
	v_lshl_add_u64 v[24:25], v[30:31], 0, v[24:25]
	global_load_dwordx4 v[24:27], v[24:25], off
	s_and_b64 vcc, exec, s[40:41]
	s_cbranch_vccnz .LBB0_1419
	global_load_dword v52, v[34:35], off offset:60
	s_branch .LBB0_1419
.Lgla_exit_prio:
	s_setprio 0
.LBB0_1520:
	v_readlane_b32 s68, v252, 0
	v_readlane_b32 s69, v252, 1
	v_readlane_b32 s78, v252, 10
	v_readlane_b32 s79, v252, 11
	v_readlane_b32 s80, v252, 12
	v_readlane_b32 s81, v252, 13
	v_readlane_b32 s68, v255, 0
	v_readlane_b32 s78, v255, 2
	v_readlane_b32 s80, v255, 4
	v_readlane_b32 s64, v255, 6
	v_readlane_b32 s46, v252, 46
	v_readlane_b32 s70, v252, 2
	v_readlane_b32 s71, v252, 3
	v_readlane_b32 s72, v252, 4
	v_readlane_b32 s73, v252, 5
	v_readlane_b32 s74, v252, 6
	v_readlane_b32 s75, v252, 7
	v_readlane_b32 s76, v252, 8
	v_readlane_b32 s77, v252, 9
	v_readlane_b32 s82, v252, 14
	v_readlane_b32 s83, v252, 15
	v_readlane_b32 s69, v255, 1
	v_readlane_b32 s79, v255, 3
	v_readlane_b32 s81, v255, 5
	v_readlane_b32 s65, v255, 7
	v_readlane_b32 s47, v252, 47
	v_readlane_b32 s67, v255, 8
	s_mov_b32 s63, 0x10000
	s_mov_b32 s93, 0x8800
	s_mov_b64 s[94:95], 0x1000
	s_cbranch_execz .LBB0_1417
